# ret_out epilogue: hoist all 64 gate ushort loads to the top, single counted wait per row (vmcnt(60))
# speedup vs baseline: 1.0026x; 1.0026x over previous
; __device__ __forceinline__ float bf1(bf16_t h) { return __uint_as_float(((unsigned)h) << 16); }
; __device__ __forceinline__ bf16_t f2bf(float f) { return (bf16_t)(pk2(f, 0.f) & 0xffffu); }
; __device__ __forceinline__ float silu_t(float x) { return x * fast_sigmoid(x); }
; __device__ __forceinline__ int crow(int r, int hi) { return (r & 3) + 8 * (r >> 2) + 4 * hi; }
; __device__ __forceinline__ void ret_out_unit(bf16_t* Qb  , const bf16_t* __restrict__ Kh, const bf16_t* __restrict__ Vh, const bf16_t* __restrict__ Sf, const bf16_t* __restrict__ Sb,
;                                              const bf16_t* Gb, float lf2, float lb2, char* lds) {
;     ...
;   bf16_t* Ow = Qb + (long)(wid * QBLK) * 1024; const bf16_t* Gw = Gb + (long)(wid * QBLK) * 512;
; #pragma unroll
;   for (int r = 0; r < 16; ++r) {
;     float ss = (o[0][r] * o[0][r] + o[1][r] * o[1][r]) + (o[2][r] * o[2][r] + o[3][r] * o[3][r]);
; #pragma unroll
;     for (int off = 1; off < 32; off <<= 1) ss += __shfl_xor(ss, off);
;     const float rs = rsqrtf(ss * (1.f / 128.f) + EPS_N); const int orow = crow(r, hi);
; #pragma unroll
;     for (int d0 = 0; d0 < 4; ++d0) { const float g = bf1(Gw[(long)orow * 512 + d0 * 32 + r32]); Ow[(long)orow * 1024 + d0 * 32 + r32] = f2bf(o[d0][r] * rs * silu_t(g)); }
.LBB0_1952:
	s_lshl_b64 s[56:57], s[56:57], 1
	s_add_u32 s6, s15, s56
	s_addc_u32 s57, s35, s57
	s_lshl_b32 s56, s70, 1
	s_add_u32 s56, s6, s56
	v_ashrrev_i32_e32 v149, 31, v148
	s_addc_u32 s57, s57, 0
	v_lshlrev_b64 v[66:67], 11, v[148:149]
	v_lshlrev_b64 v[68:69], 10, v[148:149]
	v_lshl_add_u64 v[66:67], s[4:5], 0, v[66:67]
	v_lshl_add_u64 v[68:69], s[56:57], 0, v[68:69]
	v_lshlrev_b32_e32 v146, 1, v229
	v_lshl_add_u64 v[68:69], v[68:69], 0, v[146:147]
	v_lshl_add_u64 v[66:67], v[66:67], 0, v[146:147]
	v_lshlrev_b32_e32 v146, 10, v228
	v_lshl_add_u64 v[70:71], v[68:69], 0, v[146:147]
	v_mov_b32_e32 v181, 0
	v_lshlrev_b32_e32 v180, 10, v228
	v_lshl_add_u64 v[182:183], v[68:69], 0, v[180:181]
	global_load_ushort v110, v[182:183], off
	global_load_ushort v111, v[182:183], off offset:64
	global_load_ushort v112, v[182:183], off offset:128
	global_load_ushort v113, v[182:183], off offset:192
	v_or_b32_e32 v180, 1, v228
	v_lshlrev_b32_e32 v180, 10, v180
	v_lshl_add_u64 v[182:183], v[68:69], 0, v[180:181]
	global_load_ushort v114, v[182:183], off
	global_load_ushort v115, v[182:183], off offset:64
	global_load_ushort v116, v[182:183], off offset:128
	global_load_ushort v117, v[182:183], off offset:192
	v_or_b32_e32 v180, 2, v228
	v_lshlrev_b32_e32 v180, 10, v180
	v_lshl_add_u64 v[182:183], v[68:69], 0, v[180:181]
	global_load_ushort v118, v[182:183], off
	global_load_ushort v119, v[182:183], off offset:64
	global_load_ushort v120, v[182:183], off offset:128
	global_load_ushort v121, v[182:183], off offset:192
	v_or_b32_e32 v180, 3, v228
	v_lshlrev_b32_e32 v180, 10, v180
	v_lshl_add_u64 v[182:183], v[68:69], 0, v[180:181]
	global_load_ushort v122, v[182:183], off
	global_load_ushort v123, v[182:183], off offset:64
	global_load_ushort v124, v[182:183], off offset:128
	global_load_ushort v125, v[182:183], off offset:192
	v_or_b32_e32 v180, 8, v228
	v_lshlrev_b32_e32 v180, 10, v180
	v_lshl_add_u64 v[182:183], v[68:69], 0, v[180:181]
	global_load_ushort v126, v[182:183], off
	global_load_ushort v127, v[182:183], off offset:64
	global_load_ushort v128, v[182:183], off offset:128
	global_load_ushort v129, v[182:183], off offset:192
	v_or_b32_e32 v180, 9, v228
	v_lshlrev_b32_e32 v180, 10, v180
	v_lshl_add_u64 v[182:183], v[68:69], 0, v[180:181]
	global_load_ushort v130, v[182:183], off
	global_load_ushort v131, v[182:183], off offset:64
	global_load_ushort v132, v[182:183], off offset:128
	global_load_ushort v133, v[182:183], off offset:192
	v_or_b32_e32 v180, 10, v228
	v_lshlrev_b32_e32 v180, 10, v180
	v_lshl_add_u64 v[182:183], v[68:69], 0, v[180:181]
	global_load_ushort v134, v[182:183], off
	global_load_ushort v135, v[182:183], off offset:64
	global_load_ushort v136, v[182:183], off offset:128
	global_load_ushort v137, v[182:183], off offset:192
	v_or_b32_e32 v180, 11, v228
	v_lshlrev_b32_e32 v180, 10, v180
	v_lshl_add_u64 v[182:183], v[68:69], 0, v[180:181]
	global_load_ushort v138, v[182:183], off
	global_load_ushort v139, v[182:183], off offset:64
	global_load_ushort v140, v[182:183], off offset:128
	global_load_ushort v141, v[182:183], off offset:192
	v_or_b32_e32 v180, 16, v228
	v_lshlrev_b32_e32 v180, 10, v180
	v_lshl_add_u64 v[182:183], v[68:69], 0, v[180:181]
	global_load_ushort v142, v[182:183], off
	global_load_ushort v143, v[182:183], off offset:64
	global_load_ushort v144, v[182:183], off offset:128
	global_load_ushort v145, v[182:183], off offset:192
	v_or_b32_e32 v180, 17, v228
	v_lshlrev_b32_e32 v180, 10, v180
	v_lshl_add_u64 v[182:183], v[68:69], 0, v[180:181]
	global_load_ushort v150, v[182:183], off
	global_load_ushort v151, v[182:183], off offset:64
	global_load_ushort v152, v[182:183], off offset:128
	global_load_ushort v153, v[182:183], off offset:192
	v_or_b32_e32 v180, 18, v228
	v_lshlrev_b32_e32 v180, 10, v180
	v_lshl_add_u64 v[182:183], v[68:69], 0, v[180:181]
	global_load_ushort v154, v[182:183], off
	global_load_ushort v155, v[182:183], off offset:64
	global_load_ushort v156, v[182:183], off offset:128
	global_load_ushort v157, v[182:183], off offset:192
	v_or_b32_e32 v180, 19, v228
	v_lshlrev_b32_e32 v180, 10, v180
	v_lshl_add_u64 v[182:183], v[68:69], 0, v[180:181]
	global_load_ushort v158, v[182:183], off
	global_load_ushort v159, v[182:183], off offset:64
	global_load_ushort v160, v[182:183], off offset:128
	global_load_ushort v161, v[182:183], off offset:192
	v_or_b32_e32 v180, 24, v228
	v_lshlrev_b32_e32 v180, 10, v180
	v_lshl_add_u64 v[182:183], v[68:69], 0, v[180:181]
	global_load_ushort v162, v[182:183], off
	global_load_ushort v163, v[182:183], off offset:64
	global_load_ushort v164, v[182:183], off offset:128
	global_load_ushort v165, v[182:183], off offset:192
	v_or_b32_e32 v180, 25, v228
	v_lshlrev_b32_e32 v180, 10, v180
	v_lshl_add_u64 v[182:183], v[68:69], 0, v[180:181]
	global_load_ushort v166, v[182:183], off
	global_load_ushort v167, v[182:183], off offset:64
	global_load_ushort v168, v[182:183], off offset:128
	global_load_ushort v169, v[182:183], off offset:192
	v_or_b32_e32 v180, 26, v228
	v_lshlrev_b32_e32 v180, 10, v180
	v_lshl_add_u64 v[182:183], v[68:69], 0, v[180:181]
	global_load_ushort v172, v[182:183], off
	global_load_ushort v173, v[182:183], off offset:64
	global_load_ushort v174, v[182:183], off offset:128
	global_load_ushort v175, v[182:183], off offset:192
	v_or_b32_e32 v180, 27, v228
	v_lshlrev_b32_e32 v180, 10, v180
	v_lshl_add_u64 v[182:183], v[68:69], 0, v[180:181]
	global_load_ushort v176, v[182:183], off
	global_load_ushort v177, v[182:183], off offset:64
	global_load_ushort v178, v[182:183], off offset:128
	global_load_ushort v179, v[182:183], off offset:192
	v_and_b32_e32 v78, 64, v227
	v_mov_b32_e32 v72, v34
	v_mov_b32_e32 v73, v2
	v_mov_b32_e32 v76, v35
	v_mov_b32_e32 v77, v3
	v_mov_b32_e32 v70, v50
	v_mov_b32_e32 v71, v18
	v_xor_b32_e32 v79, 1, v227
	v_mov_b32_e32 v74, v51
	v_mov_b32_e32 v75, v19
	v_add_u32_e32 v80, 64, v78
	v_pk_mul_f32 v[72:73], v[72:73], v[72:73]
	v_pk_mul_f32 v[76:77], v[76:77], v[76:77]
	v_pk_fma_f32 v[70:71], v[70:71], v[70:71], v[72:73]
	v_cmp_lt_i32_e32 vcc, v79, v80
	v_pk_fma_f32 v[74:75], v[74:75], v[74:75], v[76:77]
	v_mov_b32_e32 v77, v70
	v_cndmask_b32_e32 v72, v227, v79, vcc
	v_mov_b32_e32 v76, v74
	v_mov_b32_e32 v70, v75
	v_lshlrev_b32_e32 v72, 2, v72
	v_pk_add_f32 v[70:71], v[76:77], v[70:71]
	ds_bpermute_b32 v75, v72, v71
	ds_bpermute_b32 v74, v72, v70
	v_xor_b32_e32 v73, 2, v227
	v_cmp_lt_i32_e32 vcc, v73, v80
	v_lshlrev_b32_e32 v146, 11, v228
	v_lshl_add_u64 v[82:83], v[66:67], 0, v[146:147]
	v_cndmask_b32_e32 v73, v227, v73, vcc
	v_lshlrev_b32_e32 v73, 2, v73
	s_waitcnt lgkmcnt(0)
; __device__ __forceinline__ float bf1(bf16_t h) { return __uint_as_float(((unsigned)h) << 16); }
; __device__ __forceinline__ bf16_t f2bf(float f) { return (bf16_t)(pk2(f, 0.f) & 0xffffu); }
; __device__ __forceinline__ float silu_t(float x) { return x * fast_sigmoid(x); }
; __device__ __forceinline__ int crow(int r, int hi) { return (r & 3) + 8 * (r >> 2) + 4 * hi; }
; __device__ __forceinline__ void ret_out_unit(bf16_t* Qb  , const bf16_t* __restrict__ Kh, const bf16_t* __restrict__ Vh, const bf16_t* __restrict__ Sf, const bf16_t* __restrict__ Sb,
;                                              const bf16_t* Gb, float lf2, float lb2, char* lds) {
;     ...
;   for (int r = 0; r < 16; ++r) {
;     float ss = (o[0][r] * o[0][r] + o[1][r] * o[1][r]) + (o[2][r] * o[2][r] + o[3][r] * o[3][r]);
; #pragma unroll
;     for (int off = 1; off < 32; off <<= 1) ss += __shfl_xor(ss, off);
;     const float rs = rsqrtf(ss * (1.f / 128.f) + EPS_N); const int orow = crow(r, hi);
; #pragma unroll
;     for (int d0 = 0; d0 < 4; ++d0) { const float g = bf1(Gw[(long)orow * 512 + d0 * 32 + r32]); Ow[(long)orow * 1024 + d0 * 32 + r32] = f2bf(o[d0][r] * rs * silu_t(g)); }
	v_pk_add_f32 v[70:71], v[70:71], v[74:75]
	ds_bpermute_b32 v77, v73, v71
	ds_bpermute_b32 v76, v73, v70
	v_xor_b32_e32 v74, 4, v227
	v_cmp_lt_i32_e32 vcc, v74, v80
	v_xor_b32_e32 v75, 8, v227
	s_waitcnt lgkmcnt(0)
	v_pk_add_f32 v[70:71], v[70:71], v[76:77]
	v_cndmask_b32_e32 v74, v227, v74, vcc
	v_lshlrev_b32_e32 v74, 2, v74
	ds_bpermute_b32 v77, v74, v71
	ds_bpermute_b32 v76, v74, v70
	v_cmp_lt_i32_e32 vcc, v75, v80
	s_waitcnt lgkmcnt(0)
	v_pk_add_f32 v[70:71], v[70:71], v[76:77]
	v_cndmask_b32_e32 v75, v227, v75, vcc
	v_lshlrev_b32_e32 v75, 2, v75
	ds_bpermute_b32 v79, v75, v71
	ds_bpermute_b32 v78, v75, v70
	v_xor_b32_e32 v76, 16, v227
	v_cmp_lt_i32_e32 vcc, v76, v80
	s_waitcnt lgkmcnt(0)
	v_pk_add_f32 v[78:79], v[70:71], v[78:79]
	v_cndmask_b32_e32 v76, v227, v76, vcc
	v_lshlrev_b32_e32 v76, 2, v76
	ds_bpermute_b32 v81, v76, v79
	ds_bpermute_b32 v80, v76, v78
	v_mov_b64_e32 v[70:71], s[52:53]
	s_waitcnt lgkmcnt(0)
	v_pk_add_f32 v[78:79], v[78:79], v[80:81]
	s_nop 0
	v_pk_fma_f32 v[78:79], v[78:79], s[48:49], v[70:71] op_sel_hi:[1,0,0]
	s_waitcnt vmcnt(60)
	v_lshlrev_b32_e32 v80, 16, v110
	v_lshlrev_b32_e32 v81, 16, v111
	v_lshlrev_b32_e32 v84, 16, v112
	v_lshlrev_b32_e32 v85, 16, v113
	v_mul_f32_e32 v88, 0xbfb8aa3b, v84
	v_mul_f32_e32 v89, 0xbfb8aa3b, v85
	v_exp_f32_e32 v88, v88
	v_exp_f32_e32 v89, v89
	v_mul_f32_e32 v86, 0xbfb8aa3b, v80
	v_mul_f32_e32 v87, 0xbfb8aa3b, v81
	v_exp_f32_e32 v86, v86
	v_exp_f32_e32 v87, v87
	v_mul_f32_e32 v77, 0x4b800000, v79
	v_cmp_gt_f32_e32 vcc, s69, v79
	v_add_f32_e32 v88, 1.0, v88
	v_add_f32_e32 v89, 1.0, v89
	v_cndmask_b32_e32 v77, v79, v77, vcc
	v_rcp_f32_e32 v88, v88
	v_rcp_f32_e32 v89, v89
	v_rsq_f32_e32 v77, v77
	v_add_f32_e32 v86, 1.0, v86
	v_add_f32_e32 v87, 1.0, v87
	v_rcp_f32_e32 v86, v86
	v_rcp_f32_e32 v87, v87
	v_mul_f32_e32 v79, v88, v84
	v_mul_f32_e32 v84, v89, v85
	v_mul_f32_e32 v85, 0x45800000, v77
	v_cndmask_b32_e32 v77, v77, v85, vcc
	v_mul_f32_e32 v80, v86, v80
	v_mul_f32_e32 v81, v87, v81
	v_mul_f32_e32 v50, v50, v77
	v_mul_f32_e32 v34, v34, v77
	v_mul_f32_e32 v18, v18, v77
	v_mul_f32_e32 v2, v2, v77
	v_mul_f32_e32 v50, v80, v50
	v_mul_f32_e32 v34, v34, v81
	v_mul_f32_e32 v18, v18, v79
	v_mul_f32_e32 v2, v2, v84
	v_cmp_gt_f32_e64 s[4:5], s69, v78
	v_cvt_pk_bf16_f32 v50, v50, s0
	v_cvt_pk_bf16_f32 v34, v34, s0
	v_cvt_pk_bf16_f32 v18, v18, s0
	v_cvt_pk_bf16_f32 v2, v2, s0
	global_store_short v[82:83], v50, off
	global_store_short v[82:83], v34, off offset:64
	global_store_short v[82:83], v18, off offset:128
	global_store_short v[82:83], v2, off offset:192
	v_or_b32_e32 v2, 1, v228
	v_lshlrev_b32_e32 v146, 10, v2
	v_lshl_add_u64 v[80:81], v[68:69], 0, v[146:147]
	v_mul_f32_e32 v79, 0x4b800000, v78
	v_cndmask_b32_e64 v78, v78, v79, s[4:5]
	v_rsq_f32_e32 v80, v78
	v_lshlrev_b32_e32 v146, 11, v2
	v_lshl_add_u64 v[78:79], v[66:67], 0, v[146:147]
	v_mul_f32_e32 v2, 0x45800000, v80
	v_cndmask_b32_e64 v2, v80, v2, s[4:5]
	v_mul_f32_e32 v51, v51, v2
	v_mul_f32_e32 v35, v35, v2
	v_mul_f32_e32 v19, v19, v2
	v_mul_f32_e32 v2, v3, v2
	s_waitcnt vmcnt(60)
	v_lshlrev_b32_e32 v3, 16, v114
	v_lshlrev_b32_e32 v18, 16, v115
	v_lshlrev_b32_e32 v34, 16, v116
	v_lshlrev_b32_e32 v50, 16, v117
	v_mul_f32_e32 v77, 0xbfb8aa3b, v3
	v_mul_f32_e32 v80, 0xbfb8aa3b, v18
	v_mul_f32_e32 v81, 0xbfb8aa3b, v34
	v_mul_f32_e32 v82, 0xbfb8aa3b, v50
	v_exp_f32_e32 v77, v77
	v_exp_f32_e32 v80, v80
	v_exp_f32_e32 v81, v81
	v_exp_f32_e32 v82, v82
	v_add_f32_e32 v77, 1.0, v77
	v_add_f32_e32 v80, 1.0, v80
	v_add_f32_e32 v81, 1.0, v81
	v_add_f32_e32 v82, 1.0, v82
	v_rcp_f32_e32 v77, v77
	v_rcp_f32_e32 v80, v80
	v_rcp_f32_e32 v81, v81
	v_rcp_f32_e32 v82, v82
	v_mul_f32_e32 v3, v77, v3
	v_mul_f32_e32 v18, v80, v18
	v_mul_f32_e32 v34, v81, v34
	v_mul_f32_e32 v50, v82, v50
	v_mul_f32_e32 v3, v3, v51
	v_mul_f32_e32 v18, v35, v18
	v_mul_f32_e32 v19, v19, v34
	v_mul_f32_e32 v2, v2, v50
	v_cvt_pk_bf16_f32 v3, v3, s0
	v_cvt_pk_bf16_f32 v18, v18, s0
	v_cvt_pk_bf16_f32 v19, v19, s0
	v_cvt_pk_bf16_f32 v2, v2, s0
	global_store_short v[78:79], v3, off
	global_store_short v[78:79], v18, off offset:64
	global_store_short v[78:79], v19, off offset:128
	global_store_short v[78:79], v2, off offset:192
	v_or_b32_e32 v77, 2, v228
	v_lshlrev_b32_e32 v146, 10, v77
	v_lshl_add_u64 v[2:3], v[68:69], 0, v[146:147]
	v_mov_b32_e32 v18, v36
	v_mov_b32_e32 v19, v4
	v_mov_b32_e32 v50, v37
	v_mov_b32_e32 v51, v5
	v_mov_b32_e32 v2, v52
	v_mov_b32_e32 v3, v20
	v_mov_b32_e32 v34, v53
	v_mov_b32_e32 v35, v21
	v_pk_mul_f32 v[18:19], v[18:19], v[18:19]
	v_pk_mul_f32 v[50:51], v[50:51], v[50:51]
	v_pk_fma_f32 v[2:3], v[2:3], v[2:3], v[18:19]
	v_pk_fma_f32 v[18:19], v[34:35], v[34:35], v[50:51]
	v_mov_b32_e32 v35, v2
	v_mov_b32_e32 v34, v18
	v_mov_b32_e32 v2, v19
	v_pk_add_f32 v[2:3], v[34:35], v[2:3]
	ds_bpermute_b32 v19, v72, v3
	ds_bpermute_b32 v18, v72, v2
	v_lshlrev_b32_e32 v146, 11, v77
	s_waitcnt lgkmcnt(0)
	v_pk_add_f32 v[2:3], v[2:3], v[18:19]
	ds_bpermute_b32 v19, v73, v3
	ds_bpermute_b32 v18, v73, v2
	s_waitcnt lgkmcnt(0)
	v_pk_add_f32 v[2:3], v[2:3], v[18:19]
	ds_bpermute_b32 v19, v74, v3
	ds_bpermute_b32 v18, v74, v2
	s_waitcnt lgkmcnt(0)
	v_pk_add_f32 v[2:3], v[2:3], v[18:19]
	ds_bpermute_b32 v19, v75, v3
	ds_bpermute_b32 v18, v75, v2
	s_waitcnt lgkmcnt(0)
	v_pk_add_f32 v[2:3], v[2:3], v[18:19]
	ds_bpermute_b32 v19, v76, v3
	ds_bpermute_b32 v18, v76, v2
	s_waitcnt lgkmcnt(0)
	v_pk_add_f32 v[2:3], v[2:3], v[18:19]
	s_nop 0
	v_pk_fma_f32 v[2:3], v[2:3], s[48:49], v[70:71] op_sel_hi:[1,0,0]
	s_waitcnt vmcnt(60)
; __device__ __forceinline__ float bf1(bf16_t h) { return __uint_as_float(((unsigned)h) << 16); }
; __device__ __forceinline__ bf16_t f2bf(float f) { return (bf16_t)(pk2(f, 0.f) & 0xffffu); }
; __device__ __forceinline__ float silu_t(float x) { return x * fast_sigmoid(x); }
; __device__ __forceinline__ int crow(int r, int hi) { return (r & 3) + 8 * (r >> 2) + 4 * hi; }
; __device__ __forceinline__ void ret_out_unit(bf16_t* Qb  , const bf16_t* __restrict__ Kh, const bf16_t* __restrict__ Vh, const bf16_t* __restrict__ Sf, const bf16_t* __restrict__ Sb,
;                                              const bf16_t* Gb, float lf2, float lb2, char* lds) {
;     ...
;   for (int r = 0; r < 16; ++r) {
;     float ss = (o[0][r] * o[0][r] + o[1][r] * o[1][r]) + (o[2][r] * o[2][r] + o[3][r] * o[3][r]);
; #pragma unroll
;     for (int off = 1; off < 32; off <<= 1) ss += __shfl_xor(ss, off);
;     const float rs = rsqrtf(ss * (1.f / 128.f) + EPS_N); const int orow = crow(r, hi);
; #pragma unroll
;     for (int d0 = 0; d0 < 4; ++d0) { const float g = bf1(Gw[(long)orow * 512 + d0 * 32 + r32]); Ow[(long)orow * 1024 + d0 * 32 + r32] = f2bf(o[d0][r] * rs * silu_t(g)); }
	v_lshlrev_b32_e32 v50, 16, v120
	v_mul_f32_e32 v18, 0x4b800000, v3
	v_cmp_gt_f32_e64 s[4:5], s69, v3
	v_lshlrev_b32_e32 v51, 16, v121
	v_cmp_gt_f32_e32 vcc, s69, v2
	v_cndmask_b32_e64 v3, v3, v18, s[4:5]
	v_rsq_f32_e32 v3, v3
	v_lshl_add_u64 v[18:19], v[66:67], 0, v[146:147]
	v_mul_f32_e32 v34, 0x45800000, v3
	v_cndmask_b32_e64 v3, v3, v34, s[4:5]
	v_mul_f32_e32 v34, v52, v3
	v_mul_f32_e32 v35, v36, v3
	v_mul_f32_e32 v20, v20, v3
	v_mul_f32_e32 v3, v4, v3
	v_lshlrev_b32_e32 v4, 16, v118
	v_lshlrev_b32_e32 v36, 16, v119
	v_mul_f32_e32 v52, 0xbfb8aa3b, v4
	v_mul_f32_e32 v77, 0xbfb8aa3b, v36
	v_mul_f32_e32 v78, 0xbfb8aa3b, v50
	v_mul_f32_e32 v79, 0xbfb8aa3b, v51
	v_exp_f32_e32 v52, v52
	v_exp_f32_e32 v77, v77
	v_exp_f32_e32 v78, v78
	v_exp_f32_e32 v79, v79
	v_add_f32_e32 v52, 1.0, v52
	v_add_f32_e32 v77, 1.0, v77
	v_add_f32_e32 v78, 1.0, v78
	v_add_f32_e32 v79, 1.0, v79
	v_rcp_f32_e32 v52, v52
	v_rcp_f32_e32 v77, v77
	v_rcp_f32_e32 v78, v78
	v_rcp_f32_e32 v79, v79
	v_mul_f32_e32 v4, v52, v4
	v_mul_f32_e32 v36, v77, v36
	v_mul_f32_e32 v50, v78, v50
	v_mul_f32_e32 v51, v79, v51
	v_mul_f32_e32 v4, v4, v34
	v_mul_f32_e32 v34, v35, v36
	v_mul_f32_e32 v20, v20, v50
	v_mul_f32_e32 v3, v3, v51
	v_cvt_pk_bf16_f32 v4, v4, s0
	v_cvt_pk_bf16_f32 v34, v34, s0
	v_cvt_pk_bf16_f32 v20, v20, s0
	v_cvt_pk_bf16_f32 v3, v3, s0
	global_store_short v[18:19], v4, off
	global_store_short v[18:19], v34, off offset:64
	global_store_short v[18:19], v20, off offset:128
	global_store_short v[18:19], v3, off offset:192
	v_or_b32_e32 v3, 3, v228
	v_lshlrev_b32_e32 v146, 10, v3
	v_lshl_add_u64 v[18:19], v[68:69], 0, v[146:147]
	s_nop 0
	v_mul_f32_e32 v19, 0x4b800000, v2
	v_cndmask_b32_e32 v2, v2, v19, vcc
	v_rsq_f32_e32 v19, v2
	v_lshlrev_b32_e32 v146, 11, v3
	v_lshl_add_u64 v[2:3], v[66:67], 0, v[146:147]
	v_mul_f32_e32 v35, 0x45800000, v19
	v_cndmask_b32_e32 v19, v19, v35, vcc
	v_mul_f32_e32 v35, v53, v19
	v_mul_f32_e32 v36, v37, v19
	v_mul_f32_e32 v21, v21, v19
	v_mul_f32_e32 v5, v5, v19
	s_waitcnt vmcnt(60)
	v_lshlrev_b32_e32 v4, 16, v122
	v_lshlrev_b32_e32 v19, 16, v123
	v_lshlrev_b32_e32 v20, 16, v124
	v_lshlrev_b32_e32 v18, 16, v125
	v_mul_f32_e32 v34, 0xbfb8aa3b, v4
	v_mul_f32_e32 v37, 0xbfb8aa3b, v19
	v_mul_f32_e32 v50, 0xbfb8aa3b, v20
	v_mul_f32_e32 v51, 0xbfb8aa3b, v18
	v_exp_f32_e32 v34, v34
	v_exp_f32_e32 v37, v37
	v_exp_f32_e32 v50, v50
	v_exp_f32_e32 v51, v51
	v_add_f32_e32 v34, 1.0, v34
	v_add_f32_e32 v37, 1.0, v37
	v_add_f32_e32 v50, 1.0, v50
	v_add_f32_e32 v51, 1.0, v51
	v_rcp_f32_e32 v34, v34
	v_rcp_f32_e32 v37, v37
	v_rcp_f32_e32 v50, v50
	v_rcp_f32_e32 v51, v51
	v_mul_f32_e32 v4, v34, v4
	v_mul_f32_e32 v19, v37, v19
	v_mul_f32_e32 v20, v50, v20
	v_mul_f32_e32 v18, v51, v18
	v_mul_f32_e32 v4, v4, v35
	v_mul_f32_e32 v19, v36, v19
	v_mul_f32_e32 v20, v21, v20
	v_mul_f32_e32 v5, v5, v18
	v_cvt_pk_bf16_f32 v4, v4, s0
	v_cvt_pk_bf16_f32 v18, v19, s0
	v_cvt_pk_bf16_f32 v19, v20, s0
	v_cvt_pk_bf16_f32 v5, v5, s0
	global_store_short v[2:3], v4, off
	global_store_short v[2:3], v18, off offset:64
	global_store_short v[2:3], v19, off offset:128
	global_store_short v[2:3], v5, off offset:192
	v_or_b32_e32 v34, 8, v228
	v_lshlrev_b32_e32 v146, 10, v34
	v_lshl_add_u64 v[2:3], v[68:69], 0, v[146:147]
	v_mov_b32_e32 v4, v38
	v_mov_b32_e32 v5, v6
	v_mov_b32_e32 v20, v39
	v_mov_b32_e32 v21, v7
	v_mov_b32_e32 v2, v54
	v_mov_b32_e32 v3, v22
	v_mov_b32_e32 v18, v55
	v_mov_b32_e32 v19, v23
	v_pk_mul_f32 v[4:5], v[4:5], v[4:5]
	v_pk_mul_f32 v[20:21], v[20:21], v[20:21]
	v_pk_fma_f32 v[2:3], v[2:3], v[2:3], v[4:5]
	v_pk_fma_f32 v[4:5], v[18:19], v[18:19], v[20:21]
	v_mov_b32_e32 v19, v2
	v_mov_b32_e32 v18, v4
	v_mov_b32_e32 v2, v5
	v_pk_add_f32 v[2:3], v[18:19], v[2:3]
	ds_bpermute_b32 v5, v72, v3
	ds_bpermute_b32 v4, v72, v2
	v_lshlrev_b32_e32 v146, 11, v34
	s_waitcnt lgkmcnt(0)
	v_pk_add_f32 v[2:3], v[2:3], v[4:5]
	ds_bpermute_b32 v5, v73, v3
	ds_bpermute_b32 v4, v73, v2
	s_waitcnt lgkmcnt(0)
	v_pk_add_f32 v[2:3], v[2:3], v[4:5]
	ds_bpermute_b32 v5, v74, v3
	ds_bpermute_b32 v4, v74, v2
	s_waitcnt lgkmcnt(0)
	v_pk_add_f32 v[2:3], v[2:3], v[4:5]
	ds_bpermute_b32 v5, v75, v3
	ds_bpermute_b32 v4, v75, v2
	s_waitcnt lgkmcnt(0)
	v_pk_add_f32 v[2:3], v[2:3], v[4:5]
	ds_bpermute_b32 v5, v76, v3
	ds_bpermute_b32 v4, v76, v2
	s_waitcnt lgkmcnt(0)
	v_pk_add_f32 v[2:3], v[2:3], v[4:5]
	s_nop 0
	v_pk_fma_f32 v[2:3], v[2:3], s[48:49], v[70:71] op_sel_hi:[1,0,0]
	s_waitcnt vmcnt(60)
	v_lshlrev_b32_e32 v21, 16, v127
	v_mul_f32_e32 v4, 0x4b800000, v3
	v_cmp_gt_f32_e64 s[4:5], s69, v3
	v_lshlrev_b32_e32 v34, 16, v129
	v_mul_f32_e32 v36, 0xbfb8aa3b, v21
	v_cndmask_b32_e64 v3, v3, v4, s[4:5]
	v_rsq_f32_e32 v3, v3
	v_exp_f32_e32 v36, v36
	v_lshl_add_u64 v[4:5], v[66:67], 0, v[146:147]
	v_cmp_gt_f32_e32 vcc, s69, v2
	v_mul_f32_e32 v18, 0x45800000, v3
	v_cndmask_b32_e64 v3, v3, v18, s[4:5]
	v_mul_f32_e32 v18, v54, v3
	v_mul_f32_e32 v19, v38, v3
	v_mul_f32_e32 v20, v22, v3
	v_mul_f32_e32 v3, v6, v3
	v_lshlrev_b32_e32 v6, 16, v126
	v_lshlrev_b32_e32 v22, 16, v128
	v_mul_f32_e32 v35, 0xbfb8aa3b, v6
	v_mul_f32_e32 v37, 0xbfb8aa3b, v22
	v_mul_f32_e32 v38, 0xbfb8aa3b, v34
	v_exp_f32_e32 v35, v35
	v_exp_f32_e32 v37, v37
	v_exp_f32_e32 v38, v38
	v_add_f32_e32 v36, 1.0, v36
	v_add_f32_e32 v35, 1.0, v35
	v_add_f32_e32 v37, 1.0, v37
	v_add_f32_e32 v38, 1.0, v38
	v_rcp_f32_e32 v35, v35
	v_rcp_f32_e32 v36, v36
	v_rcp_f32_e32 v37, v37
	v_rcp_f32_e32 v38, v38
	v_mul_f32_e32 v6, v35, v6
	v_mul_f32_e32 v21, v36, v21
	v_mul_f32_e32 v22, v37, v22
	v_mul_f32_e32 v34, v38, v34
	v_mul_f32_e32 v6, v6, v18
	v_mul_f32_e32 v18, v19, v21
	v_mul_f32_e32 v19, v20, v22
	v_mul_f32_e32 v3, v3, v34
	v_cvt_pk_bf16_f32 v6, v6, s0
	v_cvt_pk_bf16_f32 v18, v18, s0
	v_cvt_pk_bf16_f32 v19, v19, s0
	v_cvt_pk_bf16_f32 v3, v3, s0
	global_store_short v[4:5], v6, off
	global_store_short v[4:5], v18, off offset:64
	global_store_short v[4:5], v19, off offset:128
	global_store_short v[4:5], v3, off offset:192
	v_or_b32_e32 v3, 9, v228
	v_lshlrev_b32_e32 v146, 10, v3
	v_lshl_add_u64 v[4:5], v[68:69], 0, v[146:147]
	s_nop 0
	v_mul_f32_e32 v5, 0x4b800000, v2
	v_cndmask_b32_e32 v2, v2, v5, vcc
	v_rsq_f32_e32 v5, v2
	v_lshlrev_b32_e32 v146, 11, v3
	v_lshl_add_u64 v[2:3], v[66:67], 0, v[146:147]
	v_mul_f32_e32 v20, 0x45800000, v5
	v_cndmask_b32_e32 v5, v5, v20, vcc
	v_mul_f32_e32 v20, v55, v5
	v_mul_f32_e32 v21, v39, v5
	v_mul_f32_e32 v22, v23, v5
	v_mul_f32_e32 v5, v7, v5
	s_waitcnt vmcnt(60)
; __device__ __forceinline__ float bf1(bf16_t h) { return __uint_as_float(((unsigned)h) << 16); }
; __device__ __forceinline__ bf16_t f2bf(float f) { return (bf16_t)(pk2(f, 0.f) & 0xffffu); }
; __device__ __forceinline__ float silu_t(float x) { return x * fast_sigmoid(x); }
; __device__ __forceinline__ int crow(int r, int hi) { return (r & 3) + 8 * (r >> 2) + 4 * hi; }
; __device__ __forceinline__ void ret_out_unit(bf16_t* Qb  , const bf16_t* __restrict__ Kh, const bf16_t* __restrict__ Vh, const bf16_t* __restrict__ Sf, const bf16_t* __restrict__ Sb,
;                                              const bf16_t* Gb, float lf2, float lb2, char* lds) {
;     ...
;   for (int r = 0; r < 16; ++r) {
;     float ss = (o[0][r] * o[0][r] + o[1][r] * o[1][r]) + (o[2][r] * o[2][r] + o[3][r] * o[3][r]);
; #pragma unroll
;     for (int off = 1; off < 32; off <<= 1) ss += __shfl_xor(ss, off);
;     const float rs = rsqrtf(ss * (1.f / 128.f) + EPS_N); const int orow = crow(r, hi);
; #pragma unroll
;     for (int d0 = 0; d0 < 4; ++d0) { const float g = bf1(Gw[(long)orow * 512 + d0 * 32 + r32]); Ow[(long)orow * 1024 + d0 * 32 + r32] = f2bf(o[d0][r] * rs * silu_t(g)); }
	v_lshlrev_b32_e32 v6, 16, v130
	v_lshlrev_b32_e32 v7, 16, v131
	v_lshlrev_b32_e32 v18, 16, v132
	v_lshlrev_b32_e32 v4, 16, v133
	v_mul_f32_e32 v19, 0xbfb8aa3b, v6
	v_mul_f32_e32 v23, 0xbfb8aa3b, v7
	v_mul_f32_e32 v34, 0xbfb8aa3b, v18
	v_mul_f32_e32 v35, 0xbfb8aa3b, v4
	v_exp_f32_e32 v19, v19
	v_exp_f32_e32 v23, v23
	v_exp_f32_e32 v34, v34
	v_exp_f32_e32 v35, v35
	v_add_f32_e32 v19, 1.0, v19
	v_add_f32_e32 v23, 1.0, v23
	v_add_f32_e32 v34, 1.0, v34
	v_add_f32_e32 v35, 1.0, v35
	v_rcp_f32_e32 v19, v19
	v_rcp_f32_e32 v23, v23
	v_rcp_f32_e32 v34, v34
	v_rcp_f32_e32 v35, v35
	v_mul_f32_e32 v6, v19, v6
	v_mul_f32_e32 v7, v23, v7
	v_mul_f32_e32 v18, v34, v18
	v_mul_f32_e32 v4, v35, v4
	v_mul_f32_e32 v6, v6, v20
	v_mul_f32_e32 v7, v21, v7
	v_mul_f32_e32 v18, v22, v18
	v_mul_f32_e32 v4, v5, v4
	v_cvt_pk_bf16_f32 v5, v6, s0
	v_cvt_pk_bf16_f32 v6, v7, s0
	v_cvt_pk_bf16_f32 v7, v18, s0
	v_cvt_pk_bf16_f32 v4, v4, s0
	global_store_short v[2:3], v5, off
	global_store_short v[2:3], v6, off offset:64
	global_store_short v[2:3], v7, off offset:128
	global_store_short v[2:3], v4, off offset:192
	v_or_b32_e32 v20, 10, v228
	v_lshlrev_b32_e32 v146, 10, v20
	v_lshl_add_u64 v[2:3], v[68:69], 0, v[146:147]
	v_mov_b32_e32 v4, v40
	v_mov_b32_e32 v5, v8
	v_mov_b32_e32 v18, v41
	v_mov_b32_e32 v19, v9
	v_mov_b32_e32 v2, v56
	v_mov_b32_e32 v3, v24
	v_mov_b32_e32 v6, v57
	v_mov_b32_e32 v7, v25
	v_pk_mul_f32 v[4:5], v[4:5], v[4:5]
	v_pk_mul_f32 v[18:19], v[18:19], v[18:19]
	v_pk_fma_f32 v[2:3], v[2:3], v[2:3], v[4:5]
	v_pk_fma_f32 v[4:5], v[6:7], v[6:7], v[18:19]
	v_mov_b32_e32 v7, v2
	v_mov_b32_e32 v6, v4
	v_mov_b32_e32 v2, v5
	v_pk_add_f32 v[2:3], v[6:7], v[2:3]
	ds_bpermute_b32 v5, v72, v3
	ds_bpermute_b32 v4, v72, v2
	v_lshlrev_b32_e32 v146, 11, v20
	s_waitcnt lgkmcnt(0)
	v_pk_add_f32 v[2:3], v[2:3], v[4:5]
	ds_bpermute_b32 v5, v73, v3
	ds_bpermute_b32 v4, v73, v2
	s_waitcnt lgkmcnt(0)
	v_pk_add_f32 v[2:3], v[2:3], v[4:5]
	ds_bpermute_b32 v5, v74, v3
	ds_bpermute_b32 v4, v74, v2
	s_waitcnt lgkmcnt(0)
	v_pk_add_f32 v[2:3], v[2:3], v[4:5]
	ds_bpermute_b32 v5, v75, v3
	ds_bpermute_b32 v4, v75, v2
	s_waitcnt lgkmcnt(0)
	v_pk_add_f32 v[2:3], v[2:3], v[4:5]
	ds_bpermute_b32 v5, v76, v3
	ds_bpermute_b32 v4, v76, v2
	s_waitcnt lgkmcnt(0)
	v_pk_add_f32 v[2:3], v[2:3], v[4:5]
	s_nop 0
	v_pk_fma_f32 v[2:3], v[2:3], s[48:49], v[70:71] op_sel_hi:[1,0,0]
	s_waitcnt vmcnt(60)
	v_lshlrev_b32_e32 v19, 16, v135
	v_mul_f32_e32 v4, 0x4b800000, v3
	v_cmp_gt_f32_e64 s[4:5], s69, v3
	v_lshlrev_b32_e32 v20, 16, v136
	v_mul_f32_e32 v23, 0xbfb8aa3b, v19
	v_cndmask_b32_e64 v3, v3, v4, s[4:5]
	v_rsq_f32_e32 v3, v3
	v_exp_f32_e32 v23, v23
	v_lshl_add_u64 v[4:5], v[66:67], 0, v[146:147]
	v_cmp_gt_f32_e32 vcc, s69, v2
	v_mul_f32_e32 v6, 0x45800000, v3
	v_cndmask_b32_e64 v3, v3, v6, s[4:5]
	v_mul_f32_e32 v6, v56, v3
	v_mul_f32_e32 v7, v40, v3
	v_mul_f32_e32 v18, v24, v3
	v_mul_f32_e32 v3, v8, v3
	v_lshlrev_b32_e32 v8, 16, v134
	v_lshlrev_b32_e32 v21, 16, v137
	v_mul_f32_e32 v22, 0xbfb8aa3b, v8
	v_mul_f32_e32 v24, 0xbfb8aa3b, v20
	v_mul_f32_e32 v34, 0xbfb8aa3b, v21
	v_exp_f32_e32 v22, v22
	v_exp_f32_e32 v24, v24
	v_exp_f32_e32 v34, v34
	v_add_f32_e32 v23, 1.0, v23
	v_add_f32_e32 v22, 1.0, v22
	v_add_f32_e32 v24, 1.0, v24
	v_add_f32_e32 v34, 1.0, v34
	v_rcp_f32_e32 v22, v22
	v_rcp_f32_e32 v23, v23
	v_rcp_f32_e32 v24, v24
	v_rcp_f32_e32 v34, v34
	v_mul_f32_e32 v8, v22, v8
	v_mul_f32_e32 v19, v23, v19
	v_mul_f32_e32 v20, v24, v20
	v_mul_f32_e32 v21, v34, v21
	v_mul_f32_e32 v6, v8, v6
	v_mul_f32_e32 v7, v7, v19
	v_mul_f32_e32 v8, v18, v20
	v_mul_f32_e32 v3, v3, v21
	v_cvt_pk_bf16_f32 v6, v6, s0
	v_cvt_pk_bf16_f32 v7, v7, s0
	v_cvt_pk_bf16_f32 v8, v8, s0
	v_cvt_pk_bf16_f32 v3, v3, s0
	global_store_short v[4:5], v6, off
	global_store_short v[4:5], v7, off offset:64
	global_store_short v[4:5], v8, off offset:128
	global_store_short v[4:5], v3, off offset:192
	v_or_b32_e32 v3, 11, v228
	v_lshlrev_b32_e32 v146, 10, v3
	v_lshl_add_u64 v[4:5], v[68:69], 0, v[146:147]
	s_nop 0
	v_mul_f32_e32 v5, 0x4b800000, v2
	v_cndmask_b32_e32 v2, v2, v5, vcc
	v_rsq_f32_e32 v5, v2
	v_lshlrev_b32_e32 v146, 11, v3
	v_lshl_add_u64 v[2:3], v[66:67], 0, v[146:147]
	v_mul_f32_e32 v18, 0x45800000, v5
	v_cndmask_b32_e32 v5, v5, v18, vcc
	v_mul_f32_e32 v18, v57, v5
	v_mul_f32_e32 v19, v41, v5
	v_mul_f32_e32 v20, v25, v5
	v_mul_f32_e32 v5, v9, v5
	s_waitcnt vmcnt(60)
	v_lshlrev_b32_e32 v6, 16, v138
	v_lshlrev_b32_e32 v7, 16, v139
	v_lshlrev_b32_e32 v8, 16, v140
	v_lshlrev_b32_e32 v4, 16, v141
	v_mul_f32_e32 v9, 0xbfb8aa3b, v6
	v_mul_f32_e32 v21, 0xbfb8aa3b, v7
	v_mul_f32_e32 v22, 0xbfb8aa3b, v8
	v_mul_f32_e32 v23, 0xbfb8aa3b, v4
	v_exp_f32_e32 v9, v9
	v_exp_f32_e32 v21, v21
	v_exp_f32_e32 v22, v22
	v_exp_f32_e32 v23, v23
	v_add_f32_e32 v9, 1.0, v9
	v_add_f32_e32 v21, 1.0, v21
	v_add_f32_e32 v22, 1.0, v22
	v_add_f32_e32 v23, 1.0, v23
	v_rcp_f32_e32 v9, v9
	v_rcp_f32_e32 v21, v21
	v_rcp_f32_e32 v22, v22
	v_rcp_f32_e32 v23, v23
	v_mul_f32_e32 v6, v9, v6
	v_mul_f32_e32 v7, v21, v7
	v_mul_f32_e32 v8, v22, v8
	v_mul_f32_e32 v4, v23, v4
	v_mul_f32_e32 v6, v6, v18
	v_mul_f32_e32 v7, v19, v7
	v_mul_f32_e32 v8, v20, v8
	v_mul_f32_e32 v4, v5, v4
	v_cvt_pk_bf16_f32 v5, v6, s0
	v_cvt_pk_bf16_f32 v6, v7, s0
	v_cvt_pk_bf16_f32 v7, v8, s0
	v_cvt_pk_bf16_f32 v4, v4, s0
	global_store_short v[2:3], v5, off
	global_store_short v[2:3], v6, off offset:64
	global_store_short v[2:3], v7, off offset:128
	global_store_short v[2:3], v4, off offset:192
	v_or_b32_e32 v18, 16, v228
	v_lshlrev_b32_e32 v146, 10, v18
	v_lshl_add_u64 v[2:3], v[68:69], 0, v[146:147]
	v_mov_b32_e32 v4, v42
	v_mov_b32_e32 v5, v10
	v_mov_b32_e32 v8, v43
	v_mov_b32_e32 v9, v11
	v_mov_b32_e32 v2, v58
	v_mov_b32_e32 v3, v26
	v_mov_b32_e32 v6, v59
	v_mov_b32_e32 v7, v27
	v_pk_mul_f32 v[4:5], v[4:5], v[4:5]
	v_pk_mul_f32 v[8:9], v[8:9], v[8:9]
	v_pk_fma_f32 v[2:3], v[2:3], v[2:3], v[4:5]
	v_pk_fma_f32 v[4:5], v[6:7], v[6:7], v[8:9]
	v_mov_b32_e32 v7, v2
	v_mov_b32_e32 v6, v4
	v_mov_b32_e32 v2, v5
	v_pk_add_f32 v[2:3], v[6:7], v[2:3]
	ds_bpermute_b32 v5, v72, v3
	ds_bpermute_b32 v4, v72, v2
	v_lshlrev_b32_e32 v146, 11, v18
	s_waitcnt lgkmcnt(0)
; __device__ __forceinline__ float bf1(bf16_t h) { return __uint_as_float(((unsigned)h) << 16); }
; __device__ __forceinline__ bf16_t f2bf(float f) { return (bf16_t)(pk2(f, 0.f) & 0xffffu); }
; __device__ __forceinline__ float silu_t(float x) { return x * fast_sigmoid(x); }
; __device__ __forceinline__ int crow(int r, int hi) { return (r & 3) + 8 * (r >> 2) + 4 * hi; }
; __device__ __forceinline__ void ret_out_unit(bf16_t* Qb  , const bf16_t* __restrict__ Kh, const bf16_t* __restrict__ Vh, const bf16_t* __restrict__ Sf, const bf16_t* __restrict__ Sb,
;                                              const bf16_t* Gb, float lf2, float lb2, char* lds) {
;     ...
;   for (int r = 0; r < 16; ++r) {
;     float ss = (o[0][r] * o[0][r] + o[1][r] * o[1][r]) + (o[2][r] * o[2][r] + o[3][r] * o[3][r]);
; #pragma unroll
;     for (int off = 1; off < 32; off <<= 1) ss += __shfl_xor(ss, off);
;     const float rs = rsqrtf(ss * (1.f / 128.f) + EPS_N); const int orow = crow(r, hi);
; #pragma unroll
;     for (int d0 = 0; d0 < 4; ++d0) { const float g = bf1(Gw[(long)orow * 512 + d0 * 32 + r32]); Ow[(long)orow * 1024 + d0 * 32 + r32] = f2bf(o[d0][r] * rs * silu_t(g)); }
	v_pk_add_f32 v[2:3], v[2:3], v[4:5]
	ds_bpermute_b32 v5, v73, v3
	ds_bpermute_b32 v4, v73, v2
	s_waitcnt lgkmcnt(0)
	v_pk_add_f32 v[2:3], v[2:3], v[4:5]
	ds_bpermute_b32 v5, v74, v3
	ds_bpermute_b32 v4, v74, v2
	s_waitcnt lgkmcnt(0)
	v_pk_add_f32 v[2:3], v[2:3], v[4:5]
	ds_bpermute_b32 v5, v75, v3
	ds_bpermute_b32 v4, v75, v2
	s_waitcnt lgkmcnt(0)
	v_pk_add_f32 v[2:3], v[2:3], v[4:5]
	ds_bpermute_b32 v5, v76, v3
	ds_bpermute_b32 v4, v76, v2
	s_waitcnt lgkmcnt(0)
	v_pk_add_f32 v[2:3], v[2:3], v[4:5]
	s_nop 0
	v_pk_fma_f32 v[2:3], v[2:3], s[48:49], v[70:71] op_sel_hi:[1,0,0]
	s_waitcnt vmcnt(60)
	v_lshlrev_b32_e32 v9, 16, v142
	v_mul_f32_e32 v4, 0x4b800000, v3
	v_cmp_gt_f32_e64 s[4:5], s69, v3
	v_lshlrev_b32_e32 v18, 16, v144
	v_lshlrev_b32_e32 v19, 16, v145
	v_cndmask_b32_e64 v3, v3, v4, s[4:5]
	v_rsq_f32_e32 v3, v3
	v_mul_f32_e32 v22, 0xbfb8aa3b, v18
	v_mul_f32_e32 v23, 0xbfb8aa3b, v19
	v_exp_f32_e32 v22, v22
	v_mul_f32_e32 v6, 0x45800000, v3
	v_cndmask_b32_e64 v3, v3, v6, s[4:5]
	v_mul_f32_e32 v6, v58, v3
	v_mul_f32_e32 v7, v42, v3
	v_mul_f32_e32 v8, v26, v3
	v_mul_f32_e32 v3, v10, v3
	v_lshlrev_b32_e32 v10, 16, v143
	v_mul_f32_e32 v20, 0xbfb8aa3b, v9
	v_mul_f32_e32 v21, 0xbfb8aa3b, v10
	v_exp_f32_e32 v20, v20
	v_exp_f32_e32 v21, v21
	v_exp_f32_e32 v23, v23
	v_add_f32_e32 v22, 1.0, v22
	v_add_f32_e32 v20, 1.0, v20
	v_add_f32_e32 v21, 1.0, v21
	v_add_f32_e32 v23, 1.0, v23
	v_rcp_f32_e32 v20, v20
	v_rcp_f32_e32 v21, v21
	v_rcp_f32_e32 v22, v22
	v_rcp_f32_e32 v23, v23
	v_mul_f32_e32 v9, v20, v9
	v_mul_f32_e32 v10, v21, v10
	v_mul_f32_e32 v18, v22, v18
	v_mul_f32_e32 v19, v23, v19
	v_mul_f32_e32 v6, v9, v6
	v_lshl_add_u64 v[4:5], v[66:67], 0, v[146:147]
	v_mul_f32_e32 v7, v7, v10
	v_mul_f32_e32 v8, v8, v18
	v_mul_f32_e32 v3, v3, v19
	v_cvt_pk_bf16_f32 v6, v6, s0
	v_cmp_gt_f32_e32 vcc, s69, v2
	v_cvt_pk_bf16_f32 v7, v7, s0
	v_cvt_pk_bf16_f32 v8, v8, s0
	v_cvt_pk_bf16_f32 v3, v3, s0
	global_store_short v[4:5], v6, off
	global_store_short v[4:5], v7, off offset:64
	global_store_short v[4:5], v8, off offset:128
	global_store_short v[4:5], v3, off offset:192
	v_or_b32_e32 v3, 17, v228
	v_lshlrev_b32_e32 v146, 10, v3
	v_lshl_add_u64 v[4:5], v[68:69], 0, v[146:147]
	s_nop 0
	v_mul_f32_e32 v5, 0x4b800000, v2
	v_cndmask_b32_e32 v2, v2, v5, vcc
	v_rsq_f32_e32 v5, v2
	v_lshlrev_b32_e32 v146, 11, v3
	v_lshl_add_u64 v[2:3], v[66:67], 0, v[146:147]
	v_mul_f32_e32 v9, 0x45800000, v5
	v_cndmask_b32_e32 v5, v5, v9, vcc
	v_mul_f32_e32 v9, v59, v5
	v_mul_f32_e32 v10, v43, v5
	v_mul_f32_e32 v18, v27, v5
	v_mul_f32_e32 v5, v11, v5
	s_waitcnt vmcnt(60)
	v_lshlrev_b32_e32 v6, 16, v150
	v_lshlrev_b32_e32 v7, 16, v151
	v_lshlrev_b32_e32 v8, 16, v152
	v_lshlrev_b32_e32 v4, 16, v153
	v_mul_f32_e32 v11, 0xbfb8aa3b, v6
	v_mul_f32_e32 v19, 0xbfb8aa3b, v7
	v_mul_f32_e32 v20, 0xbfb8aa3b, v8
	v_mul_f32_e32 v21, 0xbfb8aa3b, v4
	v_exp_f32_e32 v11, v11
	v_exp_f32_e32 v19, v19
	v_exp_f32_e32 v20, v20
	v_exp_f32_e32 v21, v21
	v_add_f32_e32 v11, 1.0, v11
	v_add_f32_e32 v19, 1.0, v19
	v_add_f32_e32 v20, 1.0, v20
	v_add_f32_e32 v21, 1.0, v21
	v_rcp_f32_e32 v11, v11
	v_rcp_f32_e32 v19, v19
	v_rcp_f32_e32 v20, v20
	v_rcp_f32_e32 v21, v21
	v_mul_f32_e32 v6, v11, v6
	v_mul_f32_e32 v7, v19, v7
	v_mul_f32_e32 v8, v20, v8
	v_mul_f32_e32 v4, v21, v4
	v_mul_f32_e32 v6, v6, v9
	v_mul_f32_e32 v7, v10, v7
	v_mul_f32_e32 v8, v18, v8
	v_mul_f32_e32 v4, v5, v4
	v_cvt_pk_bf16_f32 v5, v6, s0
	v_cvt_pk_bf16_f32 v6, v7, s0
	v_cvt_pk_bf16_f32 v7, v8, s0
	v_cvt_pk_bf16_f32 v4, v4, s0
	global_store_short v[2:3], v5, off
	global_store_short v[2:3], v6, off offset:64
	global_store_short v[2:3], v7, off offset:128
	global_store_short v[2:3], v4, off offset:192
	v_or_b32_e32 v10, 18, v228
	v_lshlrev_b32_e32 v146, 10, v10
	v_lshl_add_u64 v[2:3], v[68:69], 0, v[146:147]
	v_mov_b32_e32 v4, v44
	v_mov_b32_e32 v5, v12
	v_mov_b32_e32 v8, v45
	v_mov_b32_e32 v9, v13
	v_mov_b32_e32 v2, v60
	v_mov_b32_e32 v3, v28
	v_mov_b32_e32 v6, v61
	v_mov_b32_e32 v7, v29
	v_pk_mul_f32 v[4:5], v[4:5], v[4:5]
	v_pk_mul_f32 v[8:9], v[8:9], v[8:9]
	v_pk_fma_f32 v[2:3], v[2:3], v[2:3], v[4:5]
	v_pk_fma_f32 v[4:5], v[6:7], v[6:7], v[8:9]
	v_mov_b32_e32 v7, v2
	v_mov_b32_e32 v6, v4
	v_mov_b32_e32 v2, v5
	v_pk_add_f32 v[2:3], v[6:7], v[2:3]
	ds_bpermute_b32 v5, v72, v3
	ds_bpermute_b32 v4, v72, v2
	v_lshlrev_b32_e32 v146, 11, v10
	s_waitcnt lgkmcnt(0)
	v_pk_add_f32 v[2:3], v[2:3], v[4:5]
	ds_bpermute_b32 v5, v73, v3
	ds_bpermute_b32 v4, v73, v2
	s_waitcnt lgkmcnt(0)
	v_pk_add_f32 v[2:3], v[2:3], v[4:5]
	ds_bpermute_b32 v5, v74, v3
	ds_bpermute_b32 v4, v74, v2
	s_waitcnt lgkmcnt(0)
	v_pk_add_f32 v[2:3], v[2:3], v[4:5]
	ds_bpermute_b32 v5, v75, v3
	ds_bpermute_b32 v4, v75, v2
	s_waitcnt lgkmcnt(0)
	v_pk_add_f32 v[2:3], v[2:3], v[4:5]
	ds_bpermute_b32 v5, v76, v3
	ds_bpermute_b32 v4, v76, v2
	s_waitcnt lgkmcnt(0)
	v_pk_add_f32 v[2:3], v[2:3], v[4:5]
	s_nop 0
	v_pk_fma_f32 v[2:3], v[2:3], s[48:49], v[70:71] op_sel_hi:[1,0,0]
	s_waitcnt vmcnt(60)
; __device__ __forceinline__ float bf1(bf16_t h) { return __uint_as_float(((unsigned)h) << 16); }
; __device__ __forceinline__ bf16_t f2bf(float f) { return (bf16_t)(pk2(f, 0.f) & 0xffffu); }
; __device__ __forceinline__ float silu_t(float x) { return x * fast_sigmoid(x); }
; #define SBAR() __builtin_amdgcn_sched_barrier(0)
; __device__ __forceinline__ int crow(int r, int hi) { return (r & 3) + 8 * (r >> 2) + 4 * hi; }
; __device__ __forceinline__ void ret_out_unit(bf16_t* Qb  , const bf16_t* __restrict__ Kh, const bf16_t* __restrict__ Vh, const bf16_t* __restrict__ Sf, const bf16_t* __restrict__ Sb,
;                                              const bf16_t* Gb, float lf2, float lb2, char* lds) {
;     ...
;   for (int r = 0; r < 16; ++r) {
;     float ss = (o[0][r] * o[0][r] + o[1][r] * o[1][r]) + (o[2][r] * o[2][r] + o[3][r] * o[3][r]);
; #pragma unroll
;     for (int off = 1; off < 32; off <<= 1) ss += __shfl_xor(ss, off);
;     const float rs = rsqrtf(ss * (1.f / 128.f) + EPS_N); const int orow = crow(r, hi);
; #pragma unroll
;     for (int d0 = 0; d0 < 4; ++d0) { const float g = bf1(Gw[(long)orow * 512 + d0 * 32 + r32]); Ow[(long)orow * 1024 + d0 * 32 + r32] = f2bf(o[d0][r] * rs * silu_t(g)); }
;     SBAR();
	v_lshlrev_b32_e32 v9, 16, v154
	v_mul_f32_e32 v4, 0x4b800000, v3
	v_cmp_gt_f32_e64 s[4:5], s69, v3
	v_lshlrev_b32_e32 v10, 16, v155
	v_lshlrev_b32_e32 v11, 16, v156
	v_cndmask_b32_e64 v3, v3, v4, s[4:5]
	v_rsq_f32_e32 v3, v3
	v_mul_f32_e32 v18, 0xbfb8aa3b, v9
	v_mul_f32_e32 v19, 0xbfb8aa3b, v10
	v_exp_f32_e32 v18, v18
	v_mul_f32_e32 v6, 0x45800000, v3
	v_cndmask_b32_e64 v3, v3, v6, s[4:5]
	v_mul_f32_e32 v6, v60, v3
	v_mul_f32_e32 v7, v44, v3
	v_mul_f32_e32 v8, v28, v3
	v_mul_f32_e32 v3, v12, v3
	v_lshlrev_b32_e32 v12, 16, v157
	v_mul_f32_e32 v20, 0xbfb8aa3b, v11
	v_mul_f32_e32 v21, 0xbfb8aa3b, v12
	v_exp_f32_e32 v19, v19
	v_exp_f32_e32 v20, v20
	v_exp_f32_e32 v21, v21
	v_add_f32_e32 v18, 1.0, v18
	v_add_f32_e32 v19, 1.0, v19
	v_add_f32_e32 v20, 1.0, v20
	v_add_f32_e32 v21, 1.0, v21
	v_rcp_f32_e32 v18, v18
	v_rcp_f32_e32 v19, v19
	v_rcp_f32_e32 v20, v20
	v_rcp_f32_e32 v21, v21
	v_mul_f32_e32 v9, v18, v9
	v_mul_f32_e32 v10, v19, v10
	v_mul_f32_e32 v11, v20, v11
	v_mul_f32_e32 v12, v21, v12
	v_mul_f32_e32 v6, v9, v6
	v_lshl_add_u64 v[4:5], v[66:67], 0, v[146:147]
	v_mul_f32_e32 v7, v7, v10
	v_mul_f32_e32 v8, v8, v11
	v_mul_f32_e32 v3, v3, v12
	v_cvt_pk_bf16_f32 v6, v6, s0
	v_cmp_gt_f32_e32 vcc, s69, v2
	v_cvt_pk_bf16_f32 v7, v7, s0
	v_cvt_pk_bf16_f32 v8, v8, s0
	v_cvt_pk_bf16_f32 v3, v3, s0
	global_store_short v[4:5], v6, off
	global_store_short v[4:5], v7, off offset:64
	global_store_short v[4:5], v8, off offset:128
	global_store_short v[4:5], v3, off offset:192
	v_or_b32_e32 v3, 19, v228
	v_lshlrev_b32_e32 v146, 10, v3
	v_lshl_add_u64 v[4:5], v[68:69], 0, v[146:147]
	s_nop 0
	v_mul_f32_e32 v5, 0x4b800000, v2
	v_cndmask_b32_e32 v2, v2, v5, vcc
	v_rsq_f32_e32 v5, v2
	v_lshlrev_b32_e32 v146, 11, v3
	v_lshl_add_u64 v[2:3], v[66:67], 0, v[146:147]
	v_mul_f32_e32 v9, 0x45800000, v5
	v_cndmask_b32_e32 v5, v5, v9, vcc
	v_mul_f32_e32 v9, v61, v5
	v_mul_f32_e32 v10, v45, v5
	v_mul_f32_e32 v11, v29, v5
	v_mul_f32_e32 v5, v13, v5
	s_waitcnt vmcnt(60)
	v_lshlrev_b32_e32 v6, 16, v158
	v_lshlrev_b32_e32 v7, 16, v159
	v_lshlrev_b32_e32 v8, 16, v160
	v_lshlrev_b32_e32 v4, 16, v161
	v_mul_f32_e32 v12, 0xbfb8aa3b, v6
	v_mul_f32_e32 v13, 0xbfb8aa3b, v7
	v_mul_f32_e32 v18, 0xbfb8aa3b, v8
	v_mul_f32_e32 v19, 0xbfb8aa3b, v4
	v_exp_f32_e32 v12, v12
	v_exp_f32_e32 v13, v13
	v_exp_f32_e32 v18, v18
	v_exp_f32_e32 v19, v19
	v_add_f32_e32 v12, 1.0, v12
	v_add_f32_e32 v13, 1.0, v13
	v_add_f32_e32 v18, 1.0, v18
	v_add_f32_e32 v19, 1.0, v19
	v_rcp_f32_e32 v12, v12
	v_rcp_f32_e32 v13, v13
	v_rcp_f32_e32 v18, v18
	v_rcp_f32_e32 v19, v19
	v_mul_f32_e32 v6, v12, v6
	v_mul_f32_e32 v7, v13, v7
	v_mul_f32_e32 v8, v18, v8
	v_mul_f32_e32 v4, v19, v4
	v_mul_f32_e32 v6, v6, v9
	v_mul_f32_e32 v7, v10, v7
	v_mul_f32_e32 v8, v11, v8
	v_mul_f32_e32 v4, v5, v4
	v_cvt_pk_bf16_f32 v5, v6, s0
	v_cvt_pk_bf16_f32 v6, v7, s0
	v_cvt_pk_bf16_f32 v7, v8, s0
	v_cvt_pk_bf16_f32 v4, v4, s0
	global_store_short v[2:3], v5, off
	global_store_short v[2:3], v6, off offset:64
	global_store_short v[2:3], v7, off offset:128
	global_store_short v[2:3], v4, off offset:192
	v_or_b32_e32 v10, 24, v228
	v_lshlrev_b32_e32 v146, 10, v10
	v_lshl_add_u64 v[2:3], v[68:69], 0, v[146:147]
	v_mov_b32_e32 v4, v46
	v_mov_b32_e32 v5, v14
	v_mov_b32_e32 v8, v47
	v_mov_b32_e32 v9, v15
	v_mov_b32_e32 v2, v62
	v_mov_b32_e32 v3, v30
	v_mov_b32_e32 v6, v63
	v_mov_b32_e32 v7, v31
	v_pk_mul_f32 v[4:5], v[4:5], v[4:5]
	v_pk_mul_f32 v[8:9], v[8:9], v[8:9]
	v_pk_fma_f32 v[2:3], v[2:3], v[2:3], v[4:5]
	v_pk_fma_f32 v[4:5], v[6:7], v[6:7], v[8:9]
	v_mov_b32_e32 v7, v2
	v_mov_b32_e32 v6, v4
	v_mov_b32_e32 v2, v5
	v_pk_add_f32 v[2:3], v[6:7], v[2:3]
	ds_bpermute_b32 v5, v72, v3
	ds_bpermute_b32 v4, v72, v2
	v_lshlrev_b32_e32 v146, 11, v10
	s_waitcnt lgkmcnt(0)
	v_pk_add_f32 v[2:3], v[2:3], v[4:5]
	ds_bpermute_b32 v5, v73, v3
	ds_bpermute_b32 v4, v73, v2
	s_waitcnt lgkmcnt(0)
	v_pk_add_f32 v[2:3], v[2:3], v[4:5]
	ds_bpermute_b32 v5, v74, v3
	ds_bpermute_b32 v4, v74, v2
	s_waitcnt lgkmcnt(0)
	v_pk_add_f32 v[2:3], v[2:3], v[4:5]
	ds_bpermute_b32 v5, v75, v3
	ds_bpermute_b32 v4, v75, v2
	s_waitcnt lgkmcnt(0)
	v_pk_add_f32 v[2:3], v[2:3], v[4:5]
	ds_bpermute_b32 v5, v76, v3
	ds_bpermute_b32 v4, v76, v2
	s_waitcnt lgkmcnt(0)
	v_pk_add_f32 v[2:3], v[2:3], v[4:5]
	s_nop 0
	v_pk_fma_f32 v[2:3], v[2:3], s[48:49], v[70:71] op_sel_hi:[1,0,0]
	s_waitcnt vmcnt(60)
	v_lshlrev_b32_e32 v9, 16, v162
	v_mul_f32_e32 v4, 0x4b800000, v3
	v_cmp_gt_f32_e64 s[4:5], s69, v3
	v_lshlrev_b32_e32 v10, 16, v163
	v_lshlrev_b32_e32 v11, 16, v164
	v_cndmask_b32_e64 v3, v3, v4, s[4:5]
	v_rsq_f32_e32 v3, v3
	v_lshlrev_b32_e32 v12, 16, v165
	v_mul_f32_e32 v13, 0xbfb8aa3b, v9
	v_mul_f32_e32 v18, 0xbfb8aa3b, v11
	v_mul_f32_e32 v6, 0x45800000, v3
	v_cndmask_b32_e64 v3, v3, v6, s[4:5]
	v_mul_f32_e32 v6, v62, v3
	v_mul_f32_e32 v7, v46, v3
	v_mul_f32_e32 v8, v30, v3
	v_mul_f32_e32 v3, v14, v3
	v_mul_f32_e32 v14, 0xbfb8aa3b, v10
	v_mul_f32_e32 v19, 0xbfb8aa3b, v12
	v_exp_f32_e32 v13, v13
	v_exp_f32_e32 v14, v14
	v_exp_f32_e32 v18, v18
	v_exp_f32_e32 v19, v19
	v_add_f32_e32 v13, 1.0, v13
	v_add_f32_e32 v14, 1.0, v14
	v_add_f32_e32 v18, 1.0, v18
	v_add_f32_e32 v19, 1.0, v19
	v_rcp_f32_e32 v13, v13
	v_rcp_f32_e32 v14, v14
	v_rcp_f32_e32 v18, v18
	v_rcp_f32_e32 v19, v19
	v_mul_f32_e32 v9, v13, v9
	v_mul_f32_e32 v10, v14, v10
	v_mul_f32_e32 v11, v18, v11
	v_mul_f32_e32 v12, v19, v12
	v_mul_f32_e32 v6, v9, v6
	v_lshl_add_u64 v[4:5], v[66:67], 0, v[146:147]
	v_mul_f32_e32 v7, v7, v10
	v_mul_f32_e32 v8, v8, v11
	v_mul_f32_e32 v3, v3, v12
	v_cvt_pk_bf16_f32 v6, v6, s0
	v_cmp_gt_f32_e32 vcc, s69, v2
	v_cvt_pk_bf16_f32 v7, v7, s0
	v_cvt_pk_bf16_f32 v8, v8, s0
	v_cvt_pk_bf16_f32 v3, v3, s0
	global_store_short v[4:5], v6, off
	global_store_short v[4:5], v7, off offset:64
	global_store_short v[4:5], v8, off offset:128
	global_store_short v[4:5], v3, off offset:192
	v_or_b32_e32 v3, 25, v228
	v_lshlrev_b32_e32 v146, 10, v3
	v_lshl_add_u64 v[4:5], v[68:69], 0, v[146:147]
	s_nop 0
	v_mul_f32_e32 v5, 0x4b800000, v2
	v_cndmask_b32_e32 v2, v2, v5, vcc
	v_rsq_f32_e32 v5, v2
	v_lshlrev_b32_e32 v146, 11, v3
	v_lshl_add_u64 v[2:3], v[66:67], 0, v[146:147]
	v_mul_f32_e32 v9, 0x45800000, v5
	v_cndmask_b32_e32 v5, v5, v9, vcc
	v_mul_f32_e32 v9, v63, v5
	v_mul_f32_e32 v10, v47, v5
	v_mul_f32_e32 v11, v31, v5
	v_mul_f32_e32 v5, v15, v5
	s_waitcnt vmcnt(60)
; __device__ __forceinline__ float bf1(bf16_t h) { return __uint_as_float(((unsigned)h) << 16); }
; __device__ __forceinline__ bf16_t f2bf(float f) { return (bf16_t)(pk2(f, 0.f) & 0xffffu); }
; __device__ __forceinline__ float silu_t(float x) { return x * fast_sigmoid(x); }
; #define SBAR() __builtin_amdgcn_sched_barrier(0)
; __device__ __forceinline__ int crow(int r, int hi) { return (r & 3) + 8 * (r >> 2) + 4 * hi; }
; __device__ __forceinline__ void ret_out_unit(bf16_t* Qb  , const bf16_t* __restrict__ Kh, const bf16_t* __restrict__ Vh, const bf16_t* __restrict__ Sf, const bf16_t* __restrict__ Sb,
;                                              const bf16_t* Gb, float lf2, float lb2, char* lds) {
;     ...
;   for (int r = 0; r < 16; ++r) {
;     float ss = (o[0][r] * o[0][r] + o[1][r] * o[1][r]) + (o[2][r] * o[2][r] + o[3][r] * o[3][r]);
; #pragma unroll
;     for (int off = 1; off < 32; off <<= 1) ss += __shfl_xor(ss, off);
;     const float rs = rsqrtf(ss * (1.f / 128.f) + EPS_N); const int orow = crow(r, hi);
; #pragma unroll
;     for (int d0 = 0; d0 < 4; ++d0) { const float g = bf1(Gw[(long)orow * 512 + d0 * 32 + r32]); Ow[(long)orow * 1024 + d0 * 32 + r32] = f2bf(o[d0][r] * rs * silu_t(g)); }
;     SBAR();
;   }
;   __syncthreads();
	v_lshlrev_b32_e32 v6, 16, v166
	v_lshlrev_b32_e32 v7, 16, v167
	v_lshlrev_b32_e32 v8, 16, v168
	v_lshlrev_b32_e32 v4, 16, v169
	v_mul_f32_e32 v12, 0xbfb8aa3b, v6
	v_mul_f32_e32 v13, 0xbfb8aa3b, v7
	v_mul_f32_e32 v14, 0xbfb8aa3b, v8
	v_mul_f32_e32 v15, 0xbfb8aa3b, v4
	v_exp_f32_e32 v12, v12
	v_exp_f32_e32 v13, v13
	v_exp_f32_e32 v14, v14
	v_exp_f32_e32 v15, v15
	v_add_f32_e32 v12, 1.0, v12
	v_add_f32_e32 v13, 1.0, v13
	v_add_f32_e32 v14, 1.0, v14
	v_add_f32_e32 v15, 1.0, v15
	v_rcp_f32_e32 v12, v12
	v_rcp_f32_e32 v13, v13
	v_rcp_f32_e32 v14, v14
	v_rcp_f32_e32 v15, v15
	v_mul_f32_e32 v6, v12, v6
	v_mul_f32_e32 v7, v13, v7
	v_mul_f32_e32 v8, v14, v8
	v_mul_f32_e32 v4, v15, v4
	v_mul_f32_e32 v6, v6, v9
	v_mul_f32_e32 v7, v10, v7
	v_mul_f32_e32 v8, v11, v8
	v_mul_f32_e32 v4, v5, v4
	v_cvt_pk_bf16_f32 v5, v6, s0
	v_cvt_pk_bf16_f32 v6, v7, s0
	v_cvt_pk_bf16_f32 v7, v8, s0
	v_cvt_pk_bf16_f32 v4, v4, s0
	global_store_short v[2:3], v5, off
	global_store_short v[2:3], v6, off offset:64
	global_store_short v[2:3], v7, off offset:128
	global_store_short v[2:3], v4, off offset:192
	v_or_b32_e32 v10, 26, v228
	v_lshlrev_b32_e32 v146, 10, v10
	v_lshl_add_u64 v[2:3], v[68:69], 0, v[146:147]
	v_mov_b32_e32 v4, v48
	v_mov_b32_e32 v5, v16
	v_mov_b32_e32 v8, v49
	v_mov_b32_e32 v9, v17
	v_mov_b32_e32 v2, v64
	v_mov_b32_e32 v3, v32
	v_mov_b32_e32 v6, v65
	v_mov_b32_e32 v7, v33
	v_pk_mul_f32 v[4:5], v[4:5], v[4:5]
	v_pk_mul_f32 v[8:9], v[8:9], v[8:9]
	v_pk_fma_f32 v[2:3], v[2:3], v[2:3], v[4:5]
	v_pk_fma_f32 v[4:5], v[6:7], v[6:7], v[8:9]
	v_mov_b32_e32 v7, v2
	v_mov_b32_e32 v6, v4
	v_mov_b32_e32 v2, v5
	v_pk_add_f32 v[2:3], v[6:7], v[2:3]
	ds_bpermute_b32 v5, v72, v3
	ds_bpermute_b32 v4, v72, v2
	v_lshlrev_b32_e32 v146, 11, v10
	s_waitcnt lgkmcnt(0)
	v_pk_add_f32 v[2:3], v[2:3], v[4:5]
	ds_bpermute_b32 v5, v73, v3
	ds_bpermute_b32 v4, v73, v2
	s_waitcnt lgkmcnt(0)
	v_pk_add_f32 v[2:3], v[2:3], v[4:5]
	ds_bpermute_b32 v5, v74, v3
	ds_bpermute_b32 v4, v74, v2
	s_waitcnt lgkmcnt(0)
	v_pk_add_f32 v[2:3], v[2:3], v[4:5]
	ds_bpermute_b32 v5, v75, v3
	ds_bpermute_b32 v4, v75, v2
	s_waitcnt lgkmcnt(0)
	v_pk_add_f32 v[2:3], v[2:3], v[4:5]
	ds_bpermute_b32 v5, v76, v3
	ds_bpermute_b32 v4, v76, v2
	s_waitcnt lgkmcnt(0)
	v_pk_add_f32 v[2:3], v[2:3], v[4:5]
	s_nop 0
	v_pk_fma_f32 v[2:3], v[2:3], s[48:49], v[70:71] op_sel_hi:[1,0,0]
	s_waitcnt vmcnt(60)
	v_lshlrev_b32_e32 v9, 16, v172
	v_mul_f32_e32 v4, 0x4b800000, v3
	v_cmp_gt_f32_e64 s[4:5], s69, v3
	v_lshlrev_b32_e32 v10, 16, v173
	v_lshlrev_b32_e32 v11, 16, v174
	v_cndmask_b32_e64 v3, v3, v4, s[4:5]
	v_rsq_f32_e32 v3, v3
	v_lshlrev_b32_e32 v12, 16, v175
	v_mul_f32_e32 v13, 0xbfb8aa3b, v9
	v_mul_f32_e32 v14, 0xbfb8aa3b, v10
	v_mul_f32_e32 v6, 0x45800000, v3
	v_cndmask_b32_e64 v3, v3, v6, s[4:5]
	v_mul_f32_e32 v6, v64, v3
	v_mul_f32_e32 v7, v48, v3
	v_mul_f32_e32 v8, v32, v3
	v_mul_f32_e32 v3, v16, v3
	v_mul_f32_e32 v15, 0xbfb8aa3b, v11
	v_mul_f32_e32 v16, 0xbfb8aa3b, v12
	v_exp_f32_e32 v13, v13
	v_exp_f32_e32 v14, v14
	v_exp_f32_e32 v15, v15
	v_exp_f32_e32 v16, v16
	v_add_f32_e32 v13, 1.0, v13
	v_add_f32_e32 v14, 1.0, v14
	v_add_f32_e32 v15, 1.0, v15
	v_add_f32_e32 v16, 1.0, v16
	v_rcp_f32_e32 v13, v13
	v_rcp_f32_e32 v14, v14
	v_rcp_f32_e32 v15, v15
	v_rcp_f32_e32 v16, v16
	v_mul_f32_e32 v9, v13, v9
	v_mul_f32_e32 v10, v14, v10
	v_mul_f32_e32 v11, v15, v11
	v_mul_f32_e32 v12, v16, v12
	v_mul_f32_e32 v6, v9, v6
	v_lshl_add_u64 v[4:5], v[66:67], 0, v[146:147]
	v_mul_f32_e32 v7, v7, v10
	v_mul_f32_e32 v8, v8, v11
	v_mul_f32_e32 v3, v3, v12
	v_cvt_pk_bf16_f32 v6, v6, s0
	v_cmp_gt_f32_e32 vcc, s69, v2
	v_cvt_pk_bf16_f32 v7, v7, s0
	v_cvt_pk_bf16_f32 v8, v8, s0
	v_cvt_pk_bf16_f32 v3, v3, s0
	global_store_short v[4:5], v6, off
	global_store_short v[4:5], v7, off offset:64
	global_store_short v[4:5], v8, off offset:128
	global_store_short v[4:5], v3, off offset:192
	v_or_b32_e32 v3, 27, v228
	v_lshlrev_b32_e32 v146, 10, v3
	v_lshl_add_u64 v[4:5], v[68:69], 0, v[146:147]
	s_nop 0
	v_mul_f32_e32 v5, 0x4b800000, v2
	v_cndmask_b32_e32 v2, v2, v5, vcc
	v_rsq_f32_e32 v5, v2
	v_lshlrev_b32_e32 v146, 11, v3
	v_lshl_add_u64 v[2:3], v[66:67], 0, v[146:147]
	v_mul_f32_e32 v9, 0x45800000, v5
	v_cndmask_b32_e32 v5, v5, v9, vcc
	v_mul_f32_e32 v9, v65, v5
	v_mul_f32_e32 v10, v49, v5
	v_mul_f32_e32 v11, v33, v5
	v_mul_f32_e32 v5, v17, v5
	s_waitcnt vmcnt(60)
	v_lshlrev_b32_e32 v6, 16, v176
	v_lshlrev_b32_e32 v7, 16, v177
	v_lshlrev_b32_e32 v8, 16, v178
	v_lshlrev_b32_e32 v4, 16, v179
	v_mul_f32_e32 v12, 0xbfb8aa3b, v6
	v_mul_f32_e32 v13, 0xbfb8aa3b, v7
	v_mul_f32_e32 v14, 0xbfb8aa3b, v8
	v_mul_f32_e32 v15, 0xbfb8aa3b, v4
	v_exp_f32_e32 v12, v12
	v_exp_f32_e32 v13, v13
	v_exp_f32_e32 v14, v14
	v_exp_f32_e32 v15, v15
	v_add_f32_e32 v12, 1.0, v12
	v_add_f32_e32 v13, 1.0, v13
	v_add_f32_e32 v14, 1.0, v14
	v_add_f32_e32 v15, 1.0, v15
	v_rcp_f32_e32 v12, v12
	v_rcp_f32_e32 v13, v13
	v_rcp_f32_e32 v14, v14
	v_rcp_f32_e32 v15, v15
	v_mul_f32_e32 v6, v12, v6
	v_mul_f32_e32 v7, v13, v7
	v_mul_f32_e32 v8, v14, v8
	v_mul_f32_e32 v4, v15, v4
	v_mul_f32_e32 v6, v6, v9
	v_mul_f32_e32 v7, v10, v7
	v_mul_f32_e32 v8, v11, v8
	v_mul_f32_e32 v4, v5, v4
	v_cvt_pk_bf16_f32 v5, v6, s0
	v_cvt_pk_bf16_f32 v6, v7, s0
	v_cvt_pk_bf16_f32 v7, v8, s0
	v_cvt_pk_bf16_f32 v4, v4, s0
	global_store_short v[2:3], v5, off
	global_store_short v[2:3], v6, off offset:64
	global_store_short v[2:3], v7, off offset:128
	global_store_short v[2:3], v4, off offset:192
	s_movk_i32 s6, 0x100
	s_andn2_b64 vcc, exec, s[54:55]
	s_mov_b64 s[4:5], 0
	s_barrier
	s_cbranch_vccz .LBB0_1971
